# HGRN full-pass state-combine loop unrolled by two with swapped register sets: step i-1 loads stay in flight (vmcnt(9)) while step i is consumed, no set copies
# baseline (speedup 1.0000x reference)
; #define HG_LLOAD(I_, L_, LD_) do { const int pit_ = bh * 16 + (I_); LD_ = *(const f32x4*)(logDbuf + pit_ * 128 + 16 * wave + fq * 4); \
;                 _Pragma("unroll") for (int vt = 0; vt < 8; ++vt) L_[vt] = Lbuf[(size_t)(pit_ * 8 + vt) * 512 + tid]; } while (0)
;     ...
;             for (int i = sc - 1; i >= 0; --i) {
;                 if (i > 0) HG_LLOAD(i - 1, Lb, ldb);
.LBB0_576:
	s_ashr_i32 s25, s24, 31
	v_lshl_add_u64 v[56:57], s[24:25], 2, v[124:125]
	s_add_i32 s25, s3, s30
	s_add_i32 s80, s25, -16
	s_ashr_i32 s81, s80, 31
	s_lshl_b64 s[80:81], s[80:81], 13
	v_lshl_add_u64 v[58:59], v[126:127], 0, s[80:81]
	s_add_i32 s80, s25, -15
	s_ashr_i32 s81, s80, 31
	s_lshl_b64 s[80:81], s[80:81], 13
	v_lshl_add_u64 v[64:65], v[126:127], 0, s[80:81]
	s_add_i32 s80, s25, -14
	s_ashr_i32 s81, s80, 31
	s_lshl_b64 s[80:81], s[80:81], 13
	v_lshl_add_u64 v[68:69], v[126:127], 0, s[80:81]
	s_add_i32 s80, s25, -13
	s_ashr_i32 s81, s80, 31
	s_lshl_b64 s[80:81], s[80:81], 13
	v_lshl_add_u64 v[72:73], v[126:127], 0, s[80:81]
	s_add_i32 s80, s25, -12
	s_ashr_i32 s81, s80, 31
	s_lshl_b64 s[80:81], s[80:81], 13
	v_lshl_add_u64 v[80:81], v[126:127], 0, s[80:81]
	s_add_i32 s80, s25, -11
	s_ashr_i32 s81, s80, 31
	s_lshl_b64 s[80:81], s[80:81], 13
	v_lshl_add_u64 v[84:85], v[126:127], 0, s[80:81]
	s_add_i32 s80, s25, -10
	s_ashr_i32 s81, s80, 31
	s_lshl_b64 s[80:81], s[80:81], 13
	v_lshl_add_u64 v[88:89], v[126:127], 0, s[80:81]
	s_add_i32 s80, s25, -9
	s_ashr_i32 s81, s80, 31
	s_lshl_b64 s[80:81], s[80:81], 13
	v_lshl_add_u64 v[92:93], v[126:127], 0, s[80:81]
	global_load_dwordx4 v[60:63], v[56:57], off
	s_nop 0
	global_load_dwordx4 v[56:59], v[58:59], off
	s_nop 0
	global_load_dwordx4 v[64:67], v[64:65], off
	s_nop 0
	global_load_dwordx4 v[68:71], v[68:69], off
	s_nop 0
	global_load_dwordx4 v[72:75], v[72:73], off
	s_nop 0
	global_load_dwordx4 v[80:83], v[80:81], off
	s_nop 0
	global_load_dwordx4 v[84:87], v[84:85], off
	s_nop 0
	global_load_dwordx4 v[88:91], v[88:89], off
	s_nop 0
	global_load_dwordx4 v[92:95], v[92:93], off
	s_waitcnt vmcnt(9)
	s_branch .Lh2_c1

; __device__ __forceinline__ float fexp(float x) { return __builtin_amdgcn_exp2f(x * 1.4426950408889634f); }
; #define HG_LLOAD(I_, L_, LD_) do { const int pit_ = bh * 16 + (I_); LD_ = *(const f32x4*)(logDbuf + pit_ * 128 + 16 * wave + fq * 4); \
;                 _Pragma("unroll") for (int vt = 0; vt < 8; ++vt) L_[vt] = Lbuf[(size_t)(pit_ * 8 + vt) * 512 + tid]; } while (0)
;     ...
;             for (int i = sc - 1; i >= 0; --i) {
;                 if (i > 0) HG_LLOAD(i - 1, Lb, ldb);
;                 asm volatile("" : "+v"(La[0]), "+v"(La[1]), "+v"(La[2]), "+v"(La[3]), "+v"(La[4]), "+v"(La[5]), "+v"(La[6]), "+v"(La[7]), "+v"(lda));
;                 const f32x4 pk = (f32x4){fexp(suff[0]), fexp(suff[1]), fexp(suff[2]), fexp(suff[3])};
; #pragma unroll
;                 for (int vt = 0; vt < 8; ++vt) { S[vt] += La[vt] * pk; La[vt] = Lb[vt]; }
;                 suff += lda; lda = ldb; }
.Lh2_c1:
	v_mul_f32_e32 v0, 0x3fb8aa3b, v2
	v_mul_f32_e32 v153, 0x3fb8aa3b, v150
	v_exp_f32_e32 v152, v0
	v_mul_f32_e32 v0, 0x3fb8aa3b, v3
	v_exp_f32_e32 v154, v153
	v_mul_f32_e32 v153, 0x3fb8aa3b, v151
	v_exp_f32_e32 v155, v153
	v_exp_f32_e32 v153, v0
	s_add_i32 s30, s30, -8
	s_addk_i32 s24, 0xff80
	s_add_i32 s31, s31, -1
	s_add_i32 s39, s39, 8
	s_cmp_lt_u32 s31, 2
	v_pk_fma_f32 v[50:51], v[154:155], v[98:99], v[50:51]
	v_pk_fma_f32 v[48:49], v[152:153], v[96:97], v[48:49]
	v_pk_fma_f32 v[46:47], v[154:155], v[106:107], v[46:47]
	v_pk_fma_f32 v[44:45], v[152:153], v[104:105], v[44:45]
	v_pk_fma_f32 v[42:43], v[154:155], v[102:103], v[42:43]
	v_pk_fma_f32 v[40:41], v[152:153], v[100:101], v[40:41]
	v_pk_fma_f32 v[38:39], v[154:155], v[114:115], v[38:39]
	v_pk_fma_f32 v[36:37], v[152:153], v[112:113], v[36:37]
	v_pk_fma_f32 v[34:35], v[154:155], v[110:111], v[34:35]
	v_pk_fma_f32 v[32:33], v[152:153], v[108:109], v[32:33]
	v_pk_fma_f32 v[30:31], v[154:155], v[122:123], v[30:31]
	v_pk_fma_f32 v[28:29], v[152:153], v[120:121], v[28:29]
	v_pk_fma_f32 v[26:27], v[154:155], v[118:119], v[26:27]
	v_pk_fma_f32 v[24:25], v[152:153], v[116:117], v[24:25]
	v_pk_fma_f32 v[22:23], v[154:155], v[78:79], v[22:23]
	v_pk_fma_f32 v[20:21], v[152:153], v[76:77], v[20:21]
	v_pk_add_f32 v[150:151], v[150:151], v[54:55]
	v_pk_add_f32 v[2:3], v[2:3], v[52:53]
	s_cbranch_scc1 .LBB0_580
	s_cmp_eq_u32 s3, s39
	s_cbranch_scc1 .Lh2_w2
	s_ashr_i32 s25, s24, 31
	v_lshl_add_u64 v[96:97], s[24:25], 2, v[124:125]
	s_add_i32 s25, s3, s30
	s_add_i32 s80, s25, -16
	s_ashr_i32 s81, s80, 31
	s_lshl_b64 s[80:81], s[80:81], 13
	v_lshl_add_u64 v[98:99], v[126:127], 0, s[80:81]
	s_add_i32 s80, s25, -15
	s_ashr_i32 s81, s80, 31
	s_lshl_b64 s[80:81], s[80:81], 13
	v_lshl_add_u64 v[104:105], v[126:127], 0, s[80:81]
	s_add_i32 s80, s25, -14
	s_ashr_i32 s81, s80, 31
	s_lshl_b64 s[80:81], s[80:81], 13
	v_lshl_add_u64 v[100:101], v[126:127], 0, s[80:81]
	s_add_i32 s80, s25, -13
	s_ashr_i32 s81, s80, 31
	s_lshl_b64 s[80:81], s[80:81], 13
	v_lshl_add_u64 v[112:113], v[126:127], 0, s[80:81]
	s_add_i32 s80, s25, -12
	s_ashr_i32 s81, s80, 31
	s_lshl_b64 s[80:81], s[80:81], 13
	v_lshl_add_u64 v[108:109], v[126:127], 0, s[80:81]
	s_add_i32 s80, s25, -11
	s_ashr_i32 s81, s80, 31
	s_lshl_b64 s[80:81], s[80:81], 13
	v_lshl_add_u64 v[120:121], v[126:127], 0, s[80:81]
	s_add_i32 s80, s25, -10
	s_ashr_i32 s81, s80, 31
	s_lshl_b64 s[80:81], s[80:81], 13
	v_lshl_add_u64 v[116:117], v[126:127], 0, s[80:81]
	s_add_i32 s80, s25, -9
	s_ashr_i32 s81, s80, 31
	s_lshl_b64 s[80:81], s[80:81], 13
	v_lshl_add_u64 v[76:77], v[126:127], 0, s[80:81]
	global_load_dwordx4 v[52:55], v[96:97], off
	s_nop 0
	global_load_dwordx4 v[96:99], v[98:99], off
	s_nop 0
	global_load_dwordx4 v[104:107], v[104:105], off
	s_nop 0
	global_load_dwordx4 v[100:103], v[100:101], off
	s_nop 0
	global_load_dwordx4 v[112:115], v[112:113], off
	s_nop 0
	global_load_dwordx4 v[108:111], v[108:109], off
	s_nop 0
	global_load_dwordx4 v[120:123], v[120:121], off
	s_nop 0
	global_load_dwordx4 v[116:119], v[116:117], off
	s_nop 0
	global_load_dwordx4 v[76:79], v[76:77], off
	s_waitcnt vmcnt(9)
	s_branch .Lh2_c2

; __device__ __forceinline__ float fexp(float x) { return __builtin_amdgcn_exp2f(x * 1.4426950408889634f); }
; #define HG_LLOAD(I_, L_, LD_) do { const int pit_ = bh * 16 + (I_); LD_ = *(const f32x4*)(logDbuf + pit_ * 128 + 16 * wave + fq * 4); \
;                 _Pragma("unroll") for (int vt = 0; vt < 8; ++vt) L_[vt] = Lbuf[(size_t)(pit_ * 8 + vt) * 512 + tid]; } while (0)
;     ...
;             for (int i = sc - 1; i >= 0; --i) {
;                 if (i > 0) HG_LLOAD(i - 1, Lb, ldb);
;                 asm volatile("" : "+v"(La[0]), "+v"(La[1]), "+v"(La[2]), "+v"(La[3]), "+v"(La[4]), "+v"(La[5]), "+v"(La[6]), "+v"(La[7]), "+v"(lda));
;                 const f32x4 pk = (f32x4){fexp(suff[0]), fexp(suff[1]), fexp(suff[2]), fexp(suff[3])};
; #pragma unroll
;                 for (int vt = 0; vt < 8; ++vt) { S[vt] += La[vt] * pk; La[vt] = Lb[vt]; }
;                 suff += lda; lda = ldb; }
.Lh2_c2:
	v_mul_f32_e32 v0, 0x3fb8aa3b, v2
	v_mul_f32_e32 v153, 0x3fb8aa3b, v150
	v_exp_f32_e32 v152, v0
	v_mul_f32_e32 v0, 0x3fb8aa3b, v3
	v_exp_f32_e32 v154, v153
	v_mul_f32_e32 v153, 0x3fb8aa3b, v151
	v_exp_f32_e32 v155, v153
	v_exp_f32_e32 v153, v0
	s_add_i32 s30, s30, -8
	s_addk_i32 s24, 0xff80
	s_add_i32 s31, s31, -1
	s_add_i32 s39, s39, 8
	s_cmp_lt_u32 s31, 2
	v_pk_fma_f32 v[50:51], v[154:155], v[58:59], v[50:51]
	v_pk_fma_f32 v[48:49], v[152:153], v[56:57], v[48:49]
	v_pk_fma_f32 v[46:47], v[154:155], v[66:67], v[46:47]
	v_pk_fma_f32 v[44:45], v[152:153], v[64:65], v[44:45]
	v_pk_fma_f32 v[42:43], v[154:155], v[70:71], v[42:43]
	v_pk_fma_f32 v[40:41], v[152:153], v[68:69], v[40:41]
	v_pk_fma_f32 v[38:39], v[154:155], v[74:75], v[38:39]
	v_pk_fma_f32 v[36:37], v[152:153], v[72:73], v[36:37]
	v_pk_fma_f32 v[34:35], v[154:155], v[82:83], v[34:35]
	v_pk_fma_f32 v[32:33], v[152:153], v[80:81], v[32:33]
	v_pk_fma_f32 v[30:31], v[154:155], v[86:87], v[30:31]
	v_pk_fma_f32 v[28:29], v[152:153], v[84:85], v[28:29]
	v_pk_fma_f32 v[26:27], v[154:155], v[90:91], v[26:27]
	v_pk_fma_f32 v[24:25], v[152:153], v[88:89], v[24:25]
	v_pk_fma_f32 v[22:23], v[154:155], v[94:95], v[22:23]
	v_pk_fma_f32 v[20:21], v[152:153], v[92:93], v[20:21]
	v_pk_add_f32 v[150:151], v[150:151], v[62:63]
	v_pk_add_f32 v[2:3], v[2:3], v[60:61]
	s_cbranch_scc1 .LBB0_580
	s_cmp_eq_u32 s3, s39
	s_cbranch_scc0 .LBB0_576
	s_branch .LBB0_577
